# RWKV prompt: waves 4-7 as dedicated LDS-DMA loaders into one shared 16-slot ring (4x fewer DMA per CU), one s_barrier per chunk
# speedup vs baseline: 1.0134x; 1.0049x over previous
; #define LAS __attribute__((address_space(3)))
; #define GAS __attribute__((address_space(1)))
; #define R4_ISSUE(cc, slot) do { const GAS float* g_ = gp + (size_t)(cc) * 2048; LAS float* l_ = ring + (slot) * 1536; _Pragma("unroll") for (int i_ = 0; i_ < 6; ++i_) \
;         __builtin_amdgcn_global_load_lds((const GAS unsigned*)(g_ + off[i_]), (LAS unsigned*)(l_ + i_ * 256), 16, 0, 0); } while (0)
; #define R4_LOAD(o, sb_) do { const LAS float* sb = (sb_); (o).r = *(const LAS f32x4*)(sb + cgp * 4); (o).w = *(const LAS f32x4*)(sb + 64 + cgp * 4); (o).k = *(const LAS f32x4*)(sb + 128 + cgp * 4); \
;         (o).a = *(const LAS f32x4*)(sb + 256 + cgp * 4); (o).b = *(const LAS f32x4*)(sb + 320 + cgp * 4); (o).vv = sb[192 + rq * 4 + rl]; asm volatile("" ::: "memory"); } while (0)
; __device__ __forceinline__ void rwkv_prompt_wave4(LAS float* ring, const GAS float* RW, int mbase, int h, int rq, GAS float* Sout, GAS float* YR, int lane) {
;     const int rl = lane >> 4, cgp = lane & 15;
;     f32x2 S[2] = {{0.f, 0.f}, {0.f, 0.f}};
;     unsigned off[6];
; #pragma unroll
;     for (int i = 0; i < 6; ++i) { const int e = i * 256 + lane * 4, st = e / 384, rem = e - st * 384; off[i] = (unsigned)((rem >> 6) * SZ + st * 512 + (rem & 63)); }
;     const GAS float* gp = RW + (size_t)mbase * 512 + h * 64;
;     constexpr int NCH = SEQ / 4;
;     ...
;     struct R4Ops { f32x4 r, w, k, a, b; float vv; };
;     ...
;     for (int cc = 0; cc < 3; ++cc) R4_ISSUE(cc, cc);
;     float ykeep = 0.f;
;     R4Ops oA, oB, oC, oD;
;     asm volatile("s_waitcnt vmcnt(12)" ::: "memory");
;     R4_LOAD(oA, ring); R4_LOAD(oB, ring + 384);
.LBB0_701:
	v_readlane_b32 s68, v251, 2
	s_andn2_b64 vcc, exec, s[0:1]
	v_readlane_b32 s69, v251, 3
	s_movk_i32 s36, 0x2000
	s_movk_i32 s37, 0x4000
	s_cbranch_vccnz .LBB0_709
	v_readlane_b32 s0, v252, 16
	s_add_i32 s3, s24, s0
	s_cmpk_gt_i32 s3, 0x1ff
	s_cselect_b64 s[0:1], -1, 0
	s_or_b64 s[0:1], s[10:11], s[0:1]
	s_and_b64 vcc, exec, s[0:1]
	s_cbranch_vccnz .Lld_entry
	s_mov_b32 s14, 0
	s_waitcnt vmcnt(5)
	v_or_b32_e32 v2, 0x100, v192
	s_movk_i32 s0, 0x17f
	v_cmp_lt_u32_e32 vcc, s0, v2
	s_waitcnt vmcnt(4)
	v_mov_b32_e32 v3, 0xfffffe80
	v_and_b32_e32 v1, 60, v192
	v_cndmask_b32_e32 v3, 0, v3, vcc
	v_add_u32_e32 v2, v3, v2
	v_lshrrev_b32_e32 v2, 6, v2
	v_mov_b32_e32 v3, 0x200
	v_mul_i32_i24_e32 v2, 0x440000, v2
	v_cndmask_b32_e32 v3, 0, v3, vcc
	v_or3_b32 v46, v2, v3, v1
	v_or_b32_e32 v3, 0x400, v192
	s_waitcnt vmcnt(2)
	v_mul_u32_u24_e32 v5, 0x2ab, v3
	v_lshrrev_b32_e32 v5, 18, v5
	s_movk_i32 s0, 0xfe80
	v_mad_i32_i24 v3, v5, s0, v3
	v_lshrrev_b32_e32 v3, 6, v3
	s_mov_b32 s0, 0x440000
	v_mul_lo_u32 v3, v3, s0
	s_load_dwordx2 s[0:1], s[28:29], 0x130
	v_add_u32_e32 v2, 0x80, v192
	v_lshrrev_b32_e32 v65, 4, v191
	v_lshrrev_b32_e32 v2, 6, v2
	v_mul_u32_u24_e32 v0, 0x440000, v65
	v_mul_u32_u24_e32 v2, 0x440000, v2
	v_lshlrev_b32_e32 v52, 2, v65
	v_mov_b32_e32 v53, v17
	v_or_b32_e32 v0, v0, v1
	v_or_b32_e32 v2, v2, v1
	v_lshlrev_b32_e32 v5, 9, v5
	v_lshl_add_u64 v[54:55], s[12:13], 0, v[52:53]
	s_waitcnt lgkmcnt(0)
	s_add_u32 s12, s0, 0x4400000
	v_or_b32_e32 v4, 0x200, v2
	s_waitcnt vmcnt(1)
	v_or_b32_e32 v6, 0x400, v0
	v_or3_b32 v48, v3, v5, v1
	v_mov_b32_e32 v5, v17
	v_lshlrev_b32_e32 v8, 2, v236
	v_lshlrev_b32_e32 v67, 4, v236
	s_addc_u32 s13, s1, 0
	s_lshl_b32 s0, s24, 2
	v_readlane_b32 s1, v253, 36
	v_or_b32_e32 v50, 0x600, v2
	v_mov_b32_e32 v47, v17
	v_mov_b32_e32 v49, v17
	v_mov_b32_e32 v51, v17
	v_add_u32_e32 v68, s14, v67
	v_cmp_eq_u32_e32 vcc, 0, v236
	v_cmp_eq_u32_e64 s[4:5], 1, v236
	v_cmp_eq_u32_e64 s[6:7], 2, v236
	v_cmp_eq_u32_e64 s[8:9], 3, v236
	v_cmp_gt_u32_e64 s[40:41], 4, v236
	s_add_i32 s15, s1, s0
	v_lshlrev_b32_e32 v53, 2, v0
	v_lshlrev_b32_e32 v16, 2, v2
	v_lshlrev_b32_e32 v69, 2, v6
	v_lshlrev_b64 v[56:57], 2, v[4:5]
	v_lshlrev_b32_e32 v58, 2, v8
	s_waitcnt vmcnt(0)
	s_branch .LBB0_705

; #define R4_ISSUE(cc, slot) do { const GAS float* g_ = gp + (size_t)(cc) * 2048; LAS float* l_ = ring + (slot) * 1536; _Pragma("unroll") for (int i_ = 0; i_ < 6; ++i_) \
;         __builtin_amdgcn_global_load_lds((const GAS unsigned*)(g_ + off[i_]), (LAS unsigned*)(l_ + i_ * 256), 16, 0, 0); } while (0)
; #define R4_LOAD(o, sb_) do { const LAS float* sb = (sb_); (o).r = *(const LAS f32x4*)(sb + cgp * 4); (o).w = *(const LAS f32x4*)(sb + 64 + cgp * 4); (o).k = *(const LAS f32x4*)(sb + 128 + cgp * 4); \
;         (o).a = *(const LAS f32x4*)(sb + 256 + cgp * 4); (o).b = *(const LAS f32x4*)(sb + 320 + cgp * 4); (o).vv = sb[192 + rq * 4 + rl]; asm volatile("" ::: "memory"); } while (0)
; __device__ __forceinline__ void rwkv_prompt_wave4(LAS float* ring, const GAS float* RW, int mbase, int h, int rq, GAS float* Sout, GAS float* YR, int lane) {
;     ...
;     for (int cc = 0; cc < 3; ++cc) R4_ISSUE(cc, cc);
;     float ykeep = 0.f;
;     R4Ops oA, oB, oC, oD;
;     asm volatile("s_waitcnt vmcnt(12)" ::: "memory");
;     R4_LOAD(oA, ring); R4_LOAD(oB, ring + 384);
.LBB0_705:
	s_lshl_b32 s0, s15, 2
	s_ashr_i32 s17, s3, 7
	s_and_b32 s24, s0, 0xf0
	s_lshl_b32 s0, s17, 11
	s_bfe_u32 s16, s3, 0x30004
	s_lshl_b32 s82, s16, 8
	s_mov_b32 s21, s83
	v_mov_b32_e32 v71, 0
	v_or_b32_e32 v62, s0, v236
	v_or_b32_e32 v70, s24, v52
	v_mov_b32_e32 v44, 0
	v_mov_b32_e32 v45, v71
	s_lshl_b32 s1, s3, 2
	s_and_b32 s1, s1, 60
	v_or_b32_e32 v59, s1, v65
	v_lshl_add_u32 v42, v59, 2, s14
	s_barrier
	ds_read_b128 v[0:3], v68
	ds_read_b128 v[4:7], v68 offset:256
	ds_read_b128 v[8:11], v68 offset:512
	ds_read_b128 v[26:29], v68 offset:1024
	ds_read_b128 v[22:25], v68 offset:1280
	ds_read_b32 v64, v42 offset:768
	ds_read_b128 v[12:15], v68 offset:1536
	ds_read_b128 v[18:21], v68 offset:1792
	ds_read_b128 v[30:33], v68 offset:2048
	ds_read_b128 v[38:41], v68 offset:2560
	ds_read_b128 v[34:37], v68 offset:2816
	ds_read_b32 v66, v42 offset:2304
	s_lshl_b32 s20, s1, 2
	v_lshl_add_u64 v[42:43], v[54:55], 0, s[20:21]
	s_movk_i32 s18, 0x1800
	v_lshl_add_u64 v[60:61], v[42:43], 0, s[82:83]
	s_mov_b32 s19, 0
	s_mov_b32 s20, 1
	s_mov_b32 s21, 0
	v_mov_b32_e32 v42, 0
	v_mov_b32_e32 v43, v71
	s_branch .LBB0_707

; #define LAS __attribute__((address_space(3)))
; #define R4_ISSUE(cc, slot) do { const GAS float* g_ = gp + (size_t)(cc) * 2048; LAS float* l_ = ring + (slot) * 1536; _Pragma("unroll") for (int i_ = 0; i_ < 6; ++i_) \
;         __builtin_amdgcn_global_load_lds((const GAS unsigned*)(g_ + off[i_]), (LAS unsigned*)(l_ + i_ * 256), 16, 0, 0); } while (0)
; #define R4_LOAD(o, sb_) do { const LAS float* sb = (sb_); (o).r = *(const LAS f32x4*)(sb + cgp * 4); (o).w = *(const LAS f32x4*)(sb + 64 + cgp * 4); (o).k = *(const LAS f32x4*)(sb + 128 + cgp * 4); \
;         (o).a = *(const LAS f32x4*)(sb + 256 + cgp * 4); (o).b = *(const LAS f32x4*)(sb + 320 + cgp * 4); (o).vv = sb[192 + rq * 4 + rl]; asm volatile("" ::: "memory"); } while (0)
; __device__ __forceinline__ void rwkv_prompt_wave4(LAS float* ring, const GAS float* RW, int mbase, int h, int rq, GAS float* Sout, GAS float* YR, int lane) {
;     ...
;     for (int ci = 0; ci < NCH; ++ci) {
;         { const int cn = ci + 3; const int cl = cn < NCH ? cn : NCH - 1; R4_ISSUE(cl, cn % R4_NS); }
;         const LAS float* cb = ring + (ci % R4_NS) * 1536; const LAS float* nb = ring + ((ci + 1) % R4_NS) * 1536;
;         R4_LOAD(oC, cb + 768);  R4_STEP(oA, 0);
;         R4_LOAD(oD, cb + 1152); R4_STEP(oB, 1);
;         asm volatile("s_waitcnt vmcnt(12)" ::: "memory");
;         R4_LOAD(oA, nb);        R4_STEP(oC, 2);
;         R4_LOAD(oB, nb + 384);  R4_STEP(oD, 3);
;         if (cgp < 4) YR[(size_t)(mbase + ci * 4 + cgp) * 512 + h * 64 + rq * 4 + rl] = ykeep;
.LBB0_707:
	s_barrier
	s_lshr_b32 s0, s20, 4
	s_mul_i32 s0, s0, 0x18000
	v_subrev_u32_e32 v63, s0, v70
	v_subrev_u32_e32 v109, s0, v67
	s_lshr_b32 s0, s21, 4
	s_mul_i32 s0, s0, 0x18000
	v_subrev_u32_e32 v88, s0, v70
	v_subrev_u32_e32 v74, s0, v67
	s_waitcnt lgkmcnt(6)
	v_pk_mul_f32 v[28:29], v[44:45], v[28:29]
	s_add_i32 s0, s14, s19
	v_pk_fma_f32 v[26:27], v[42:43], v[26:27], v[28:29]
	v_add_u32_e32 v104, s0, v74
	v_add_f32_e32 v26, v26, v27
	ds_read_b128 v[72:75], v104 offset:3072
	ds_read_b128 v[76:79], v104 offset:3328
	v_add_f32_dpp v26, v26, v26 quad_perm:[1,0,3,2] row_mask:0xf bank_mask:0xf bound_ctrl:1
	ds_read_b128 v[80:83], v104 offset:3584
	ds_read_b128 v[84:87], v104 offset:4096
	v_add_f32_dpp v26, v26, v26 quad_perm:[2,3,0,1] row_mask:0xf bank_mask:0xf bound_ctrl:1
	s_nop 1
	v_add_f32_dpp v26, v26, v26 row_half_mirror row_mask:0xf bank_mask:0xf bound_ctrl:1
	s_nop 1
	v_add_f32_dpp v26, v26, v26 row_mirror row_mask:0xf bank_mask:0xf bound_ctrl:1
	v_pk_mul_f32 v[22:23], v[22:23], v[26:27] op_sel_hi:[1,0]
	v_add_u32_e32 v110, s0, v88
	v_pk_fma_f32 v[8:9], v[64:65], v[8:9], v[22:23] op_sel_hi:[0,1,1]
	v_pk_fma_f32 v[4:5], v[42:43], v[4:5], v[8:9]
	v_pk_mul_f32 v[8:9], v[24:25], v[26:27] op_sel_hi:[1,0]
	ds_read_b128 v[88:91], v104 offset:4352
	ds_read_b32 v108, v110 offset:3840
	v_pk_fma_f32 v[8:9], v[64:65], v[10:11], v[8:9] op_sel_hi:[0,1,1]
	v_pk_fma_f32 v[6:7], v[44:45], v[6:7], v[8:9]
	ds_read_b128 v[92:95], v104 offset:4608
	ds_read_b128 v[42:45], v104 offset:4864
	ds_read_b128 v[96:99], v104 offset:5120
	ds_read_b128 v[100:103], v104 offset:5632
	ds_read_b128 v[104:107], v104 offset:5888
	ds_read_b32 v110, v110 offset:5376
	s_waitcnt lgkmcnt(12)
	v_pk_mul_f32 v[2:3], v[2:3], v[6:7]
	v_pk_mul_f32 v[40:41], v[40:41], v[6:7]
	v_add_u32_e32 v63, s0, v63
	v_pk_fma_f32 v[0:1], v[0:1], v[4:5], v[2:3]
	v_pk_fma_f32 v[38:39], v[38:39], v[4:5], v[40:41]
	v_add_f32_e32 v0, v0, v1
	s_nop 0
	v_add_f32_e32 v38, v38, v39
	s_nop 0
	v_add_f32_dpp v0, v0, v0 quad_perm:[1,0,3,2] row_mask:0xf bank_mask:0xf bound_ctrl:1
	v_add_f32_dpp v38, v38, v38 quad_perm:[1,0,3,2] row_mask:0xf bank_mask:0xf bound_ctrl:1
	s_nop 0
	v_add_f32_dpp v0, v0, v0 quad_perm:[2,3,0,1] row_mask:0xf bank_mask:0xf bound_ctrl:1
	v_add_f32_dpp v38, v38, v38 quad_perm:[2,3,0,1] row_mask:0xf bank_mask:0xf bound_ctrl:1
	s_nop 0
	v_add_f32_dpp v0, v0, v0 row_half_mirror row_mask:0xf bank_mask:0xf bound_ctrl:1
	v_add_f32_dpp v38, v38, v38 row_half_mirror row_mask:0xf bank_mask:0xf bound_ctrl:1
	s_nop 0
	v_add_f32_dpp v0, v0, v0 row_mirror row_mask:0xf bank_mask:0xf bound_ctrl:1
	v_add_f32_dpp v38, v38, v38 row_mirror row_mask:0xf bank_mask:0xf bound_ctrl:1
	v_cndmask_b32_e32 v8, v71, v0, vcc
	v_pk_mul_f32 v[2:3], v[34:35], v[38:39] op_sel_hi:[1,0]
	v_pk_mul_f32 v[0:1], v[36:37], v[38:39] op_sel_hi:[1,0]
	v_pk_fma_f32 v[2:3], v[66:67], v[30:31], v[2:3] op_sel_hi:[0,1,1]
	v_pk_fma_f32 v[0:1], v[66:67], v[32:33], v[0:1] op_sel_hi:[0,1,1]
	v_pk_fma_f32 v[20:21], v[20:21], v[6:7], v[0:1]
	v_pk_fma_f32 v[18:19], v[18:19], v[4:5], v[2:3]
	v_pk_mul_f32 v[0:1], v[14:15], v[20:21]
	v_add_u32_e32 v34, s0, v109
	v_pk_fma_f32 v[0:1], v[12:13], v[18:19], v[0:1]
	s_waitcnt lgkmcnt(0)
	v_pk_mul_f32 v[12:13], v[86:87], v[20:21]
	v_add_f32_e32 v0, v0, v1
	v_pk_fma_f32 v[12:13], v[84:85], v[18:19], v[12:13]
	s_nop 0
	v_add_f32_e32 v12, v12, v13
	v_add_f32_dpp v0, v0, v0 quad_perm:[1,0,3,2] row_mask:0xf bank_mask:0xf bound_ctrl:1
	s_nop 0
	v_add_f32_dpp v12, v12, v12 quad_perm:[1,0,3,2] row_mask:0xf bank_mask:0xf bound_ctrl:1
	v_add_f32_dpp v0, v0, v0 quad_perm:[2,3,0,1] row_mask:0xf bank_mask:0xf bound_ctrl:1
	s_nop 0
	v_add_f32_dpp v12, v12, v12 quad_perm:[2,3,0,1] row_mask:0xf bank_mask:0xf bound_ctrl:1
	v_add_f32_dpp v0, v0, v0 row_half_mirror row_mask:0xf bank_mask:0xf bound_ctrl:1
	s_nop 0
	v_add_f32_dpp v12, v12, v12 row_half_mirror row_mask:0xf bank_mask:0xf bound_ctrl:1
	v_add_f32_dpp v0, v0, v0 row_mirror row_mask:0xf bank_mask:0xf bound_ctrl:1
	v_cndmask_b32_e64 v30, v8, v0, s[4:5]
	v_add_f32_dpp v12, v12, v12 row_mirror row_mask:0xf bank_mask:0xf bound_ctrl:1
	v_pk_mul_f32 v[14:15], v[88:89], v[12:13] op_sel_hi:[1,0]
	v_pk_mul_f32 v[12:13], v[90:91], v[12:13] op_sel_hi:[1,0]
	v_pk_fma_f32 v[14:15], v[80:81], v[108:109], v[14:15] op_sel_hi:[1,0,1]
	v_pk_fma_f32 v[12:13], v[82:83], v[108:109], v[12:13] op_sel_hi:[1,0,1]
	v_pk_fma_f32 v[76:77], v[76:77], v[18:19], v[14:15]
	v_pk_fma_f32 v[78:79], v[78:79], v[20:21], v[12:13]
	ds_read_b128 v[0:3], v34 offset:6144
	v_pk_mul_f32 v[12:13], v[74:75], v[78:79]
	ds_read_b128 v[4:7], v34 offset:6400
	v_pk_fma_f32 v[12:13], v[72:73], v[76:77], v[12:13]
	ds_read_b128 v[8:11], v34 offset:6656
	v_pk_mul_f32 v[72:73], v[102:103], v[78:79]
	v_add_f32_e32 v12, v12, v13
	v_pk_fma_f32 v[72:73], v[100:101], v[76:77], v[72:73]
	ds_read_b128 v[26:29], v34 offset:7168
	v_add_f32_e32 v72, v72, v73
	ds_read_b128 v[22:25], v34 offset:7424
	v_add_f32_dpp v12, v12, v12 quad_perm:[1,0,3,2] row_mask:0xf bank_mask:0xf bound_ctrl:1
	ds_read_b32 v64, v63 offset:6912
	v_add_f32_dpp v72, v72, v72 quad_perm:[1,0,3,2] row_mask:0xf bank_mask:0xf bound_ctrl:1
	s_nop 0
	v_add_f32_dpp v12, v12, v12 quad_perm:[2,3,0,1] row_mask:0xf bank_mask:0xf bound_ctrl:1
	v_add_f32_dpp v72, v72, v72 quad_perm:[2,3,0,1] row_mask:0xf bank_mask:0xf bound_ctrl:1
	s_nop 0
	v_add_f32_dpp v12, v12, v12 row_half_mirror row_mask:0xf bank_mask:0xf bound_ctrl:1
	v_add_f32_dpp v72, v72, v72 row_half_mirror row_mask:0xf bank_mask:0xf bound_ctrl:1
	s_nop 0
	v_add_f32_dpp v12, v12, v12 row_mirror row_mask:0xf bank_mask:0xf bound_ctrl:1
	v_add_f32_dpp v72, v72, v72 row_mirror row_mask:0xf bank_mask:0xf bound_ctrl:1
	v_cndmask_b32_e64 v71, v30, v12, s[6:7]
	v_pk_mul_f32 v[74:75], v[104:105], v[72:73] op_sel_hi:[1,0]
	v_pk_mul_f32 v[72:73], v[106:107], v[72:73] op_sel_hi:[1,0]
	v_pk_fma_f32 v[74:75], v[96:97], v[110:111], v[74:75] op_sel_hi:[1,0,1]
	v_pk_fma_f32 v[72:73], v[98:99], v[110:111], v[72:73] op_sel_hi:[1,0,1]
	v_pk_fma_f32 v[42:43], v[42:43], v[76:77], v[74:75]
	v_pk_fma_f32 v[44:45], v[44:45], v[78:79], v[72:73]
	ds_read_b128 v[12:15], v34 offset:7680
	v_pk_mul_f32 v[72:73], v[94:95], v[44:45]
	ds_read_b128 v[18:21], v34 offset:7936
	v_pk_fma_f32 v[72:73], v[92:93], v[42:43], v[72:73]
	ds_read_b128 v[30:33], v34 offset:8192
	v_add_f32_e32 v72, v72, v73
	ds_read_b128 v[38:41], v34 offset:8704
	ds_read_b128 v[34:37], v34 offset:8960
	v_add_f32_dpp v72, v72, v72 quad_perm:[1,0,3,2] row_mask:0xf bank_mask:0xf bound_ctrl:1
	ds_read_b32 v66, v63 offset:8448
	s_nop 0
	v_add_f32_dpp v72, v72, v72 quad_perm:[2,3,0,1] row_mask:0xf bank_mask:0xf bound_ctrl:1
	s_nop 1
	v_add_f32_dpp v72, v72, v72 row_half_mirror row_mask:0xf bank_mask:0xf bound_ctrl:1
	s_nop 1
	v_add_f32_dpp v72, v72, v72 row_mirror row_mask:0xf bank_mask:0xf bound_ctrl:1
	v_cndmask_b32_e64 v71, v71, v72, s[8:9]
	s_and_saveexec_b64 s[0:1], s[40:41]
	s_cbranch_execz .LBB0_706
; #define GAS __attribute__((address_space(1)))
; #define R4_ISSUE(cc, slot) do { const GAS float* g_ = gp + (size_t)(cc) * 2048; LAS float* l_ = ring + (slot) * 1536; _Pragma("unroll") for (int i_ = 0; i_ < 6; ++i_) \
;         __builtin_amdgcn_global_load_lds((const GAS unsigned*)(g_ + off[i_]), (LAS unsigned*)(l_ + i_ * 256), 16, 0, 0); } while (0)
; #define R4_LOAD(o, sb_) do { const LAS float* sb = (sb_); (o).r = *(const LAS f32x4*)(sb + cgp * 4); (o).w = *(const LAS f32x4*)(sb + 64 + cgp * 4); (o).k = *(const LAS f32x4*)(sb + 128 + cgp * 4); \
;         (o).a = *(const LAS f32x4*)(sb + 256 + cgp * 4); (o).b = *(const LAS f32x4*)(sb + 320 + cgp * 4); (o).vv = sb[192 + rq * 4 + rl]; asm volatile("" ::: "memory"); } while (0)
; __device__ __forceinline__ void rwkv_prompt_wave4(LAS float* ring, const GAS float* RW, int mbase, int h, int rq, GAS float* Sout, GAS float* YR, int lane) {
;     ...
;     unsigned off[6];
; #pragma unroll
;     for (int i = 0; i < 6; ++i) { const int e = i * 256 + lane * 4, st = e / 384, rem = e - st * 384; off[i] = (unsigned)((rem >> 6) * SZ + st * 512 + (rem & 63)); }
;     const GAS float* gp = RW + (size_t)mbase * 512 + h * 64;
;     constexpr int NCH = SEQ / 4;
;     ...
;     for (int cc = 0; cc < 3; ++cc) R4_ISSUE(cc, cc);
;     float ykeep = 0.f;
;     R4Ops oA, oB, oC, oD;
;     asm volatile("s_waitcnt vmcnt(12)" ::: "memory");
;     R4_LOAD(oA, ring); R4_LOAD(oB, ring + 384);
;     for (int ci = 0; ci < NCH; ++ci) {
;         { const int cn = ci + 3; const int cl = cn < NCH ? cn : NCH - 1; R4_ISSUE(cl, cn % R4_NS); }
	v_ashrrev_i32_e32 v63, 31, v62
	v_lshlrev_b64 v[72:73], 11, v[62:63]
	v_lshl_add_u64 v[72:73], v[60:61], 0, v[72:73]
	global_store_dword v[72:73], v71, off
	s_branch .LBB0_706
.Lld_entry:
	s_cmp_lt_u32 s24, 4
	s_cbranch_scc1 .LBB0_709
	v_readlane_b32 s0, v251, 4
	s_load_dwordx2 s[6:7], s[68:69], 0x138
	s_nop 3
	s_sub_u32 s1, s24, 4
	s_lshl_b32 s2, s0, 2
	s_lshr_b32 s3, s2, 7
	s_bfe_u32 s12, s2, 0x30004
	v_and_b32_e32 v0, 63, v195
	v_lshlrev_b32_e32 v0, 2, v0
	v_mov_b32_e32 v1, v0
	v_lshrrev_b32_e32 v2, 7, v1
	v_mul_u32_u24_e32 v3, 11, v2
	v_lshrrev_b32_e32 v3, 5, v3
	v_mul_u32_u24_e32 v4, 0x180, v3
	v_sub_u32_e32 v4, v1, v4
	v_lshrrev_b32_e32 v5, 6, v4
	v_and_b32_e32 v6, 63, v4
	v_lshlrev_b32_e32 v6, 2, v6
	v_lshl_add_u32 v6, v3, 11, v6
	s_mov_b32 s8, 0x1100000
	v_mul_lo_u32 v5, v5, s8
	v_add_u32_e32 v20, v5, v6
	v_add_u32_e32 v1, 0x100, v0
	v_lshrrev_b32_e32 v2, 7, v1
	v_mul_u32_u24_e32 v3, 11, v2
	v_lshrrev_b32_e32 v3, 5, v3
	v_mul_u32_u24_e32 v4, 0x180, v3
	v_sub_u32_e32 v4, v1, v4
	v_lshrrev_b32_e32 v5, 6, v4
	v_and_b32_e32 v6, 63, v4
	v_lshlrev_b32_e32 v6, 2, v6
	v_lshl_add_u32 v6, v3, 11, v6
	s_mov_b32 s8, 0x1100000
	v_mul_lo_u32 v5, v5, s8
	v_add_u32_e32 v21, v5, v6
	v_add_u32_e32 v1, 0x200, v0
	v_lshrrev_b32_e32 v2, 7, v1
	v_mul_u32_u24_e32 v3, 11, v2
	v_lshrrev_b32_e32 v3, 5, v3
	v_mul_u32_u24_e32 v4, 0x180, v3
	v_sub_u32_e32 v4, v1, v4
	v_lshrrev_b32_e32 v5, 6, v4
	v_and_b32_e32 v6, 63, v4
	v_lshlrev_b32_e32 v6, 2, v6
	v_lshl_add_u32 v6, v3, 11, v6
	s_mov_b32 s8, 0x1100000
	v_mul_lo_u32 v5, v5, s8
	v_add_u32_e32 v22, v5, v6
	v_add_u32_e32 v1, 0x300, v0
	v_lshrrev_b32_e32 v2, 7, v1
	v_mul_u32_u24_e32 v3, 11, v2
	v_lshrrev_b32_e32 v3, 5, v3
	v_mul_u32_u24_e32 v4, 0x180, v3
	v_sub_u32_e32 v4, v1, v4
	v_lshrrev_b32_e32 v5, 6, v4
	v_and_b32_e32 v6, 63, v4
	v_lshlrev_b32_e32 v6, 2, v6
	v_lshl_add_u32 v6, v3, 11, v6
	s_mov_b32 s8, 0x1100000
	v_mul_lo_u32 v5, v5, s8
	v_add_u32_e32 v23, v5, v6
	v_add_u32_e32 v1, 0x400, v0
	v_lshrrev_b32_e32 v2, 7, v1
	v_mul_u32_u24_e32 v3, 11, v2
	v_lshrrev_b32_e32 v3, 5, v3
	v_mul_u32_u24_e32 v4, 0x180, v3
	v_sub_u32_e32 v4, v1, v4
	v_lshrrev_b32_e32 v5, 6, v4
	v_and_b32_e32 v6, 63, v4
	v_lshlrev_b32_e32 v6, 2, v6
	v_lshl_add_u32 v6, v3, 11, v6
	s_mov_b32 s8, 0x1100000
	v_mul_lo_u32 v5, v5, s8
	v_add_u32_e32 v24, v5, v6
	v_add_u32_e32 v1, 0x500, v0
	v_lshrrev_b32_e32 v2, 7, v1
	v_mul_u32_u24_e32 v3, 11, v2
	v_lshrrev_b32_e32 v3, 5, v3
	v_mul_u32_u24_e32 v4, 0x180, v3
	v_sub_u32_e32 v4, v1, v4
	v_lshrrev_b32_e32 v5, 6, v4
	v_and_b32_e32 v6, 63, v4
	v_lshlrev_b32_e32 v6, 2, v6
	v_lshl_add_u32 v6, v3, 11, v6
	s_mov_b32 s8, 0x1100000
	v_mul_lo_u32 v5, v5, s8
	v_add_u32_e32 v25, v5, v6
	s_waitcnt lgkmcnt(0)
	s_add_u32 s4, s6, 0x1ad00000
	s_addc_u32 s5, s7, 0
	s_lshl_b32 s3, s3, 22
	s_add_u32 s4, s4, s3
	s_addc_u32 s5, s5, 0
	s_lshl_b32 s12, s12, 8
	s_add_u32 s4, s4, s12
	s_addc_u32 s5, s5, 0
	s_add_u32 s2, s1, 0
	s_mov_b32 s3, s2
	s_lshl_b32 s3, s3, 13
	s_add_u32 s8, s4, s3
	s_addc_u32 s9, s5, 0
	s_and_b32 s2, s2, 15
	s_mul_i32 s2, s2, 0x1800
	s_mov_b32 m0, s2
	s_nop 0
	global_load_lds_dwordx4 v20, s[8:9]
	s_add_i32 m0, s2, 0x400
	s_nop 0
	global_load_lds_dwordx4 v21, s[8:9]
	s_add_i32 m0, s2, 0x800
	s_nop 0
	global_load_lds_dwordx4 v22, s[8:9]
	s_add_i32 m0, s2, 0xc00
	s_nop 0
	global_load_lds_dwordx4 v23, s[8:9]
	s_add_i32 m0, s2, 0x1000
	s_nop 0
	global_load_lds_dwordx4 v24, s[8:9]
	s_add_i32 m0, s2, 0x1400
	s_nop 0
	global_load_lds_dwordx4 v25, s[8:9]
	s_add_u32 s2, s1, 4
	s_mov_b32 s3, s2
	s_lshl_b32 s3, s3, 13
	s_add_u32 s8, s4, s3
	s_addc_u32 s9, s5, 0
	s_and_b32 s2, s2, 15
	s_mul_i32 s2, s2, 0x1800
	s_mov_b32 m0, s2
	s_nop 0
	global_load_lds_dwordx4 v20, s[8:9]
	s_add_i32 m0, s2, 0x400
	s_nop 0
	global_load_lds_dwordx4 v21, s[8:9]
	s_add_i32 m0, s2, 0x800
	s_nop 0
	global_load_lds_dwordx4 v22, s[8:9]
	s_add_i32 m0, s2, 0xc00
	s_nop 0
	global_load_lds_dwordx4 v23, s[8:9]
	s_add_i32 m0, s2, 0x1000
	s_nop 0
	global_load_lds_dwordx4 v24, s[8:9]
	s_add_i32 m0, s2, 0x1400
	s_nop 0
	global_load_lds_dwordx4 v25, s[8:9]
	s_add_u32 s2, s1, 8
	s_mov_b32 s3, s2
	s_lshl_b32 s3, s3, 13
	s_add_u32 s8, s4, s3
	s_addc_u32 s9, s5, 0
	s_and_b32 s2, s2, 15
	s_mul_i32 s2, s2, 0x1800
	s_mov_b32 m0, s2
	s_nop 0
	global_load_lds_dwordx4 v20, s[8:9]
	s_add_i32 m0, s2, 0x400
	s_nop 0
	global_load_lds_dwordx4 v21, s[8:9]
	s_add_i32 m0, s2, 0x800
	s_nop 0
	global_load_lds_dwordx4 v22, s[8:9]
	s_add_i32 m0, s2, 0xc00
	s_nop 0
	global_load_lds_dwordx4 v23, s[8:9]
	s_add_i32 m0, s2, 0x1000
	s_nop 0
	global_load_lds_dwordx4 v24, s[8:9]
	s_add_i32 m0, s2, 0x1400
	s_nop 0
	global_load_lds_dwordx4 v25, s[8:9]
	s_mov_b32 s14, 0
.Lld_loop:
	s_and_b32 s0, s14, 3
	s_cmp_lg_u32 s0, s1
	s_cbranch_scc1 .Lld_bar
	s_waitcnt vmcnt(12)
.Lld_bar:
	s_barrier
	s_cmp_lg_u32 s0, s1
	s_cbranch_scc1 .Lld_next
	s_add_u32 s2, s14, 12
	s_min_u32 s3, s2, 0x1ff
	s_lshl_b32 s3, s3, 13
	s_add_u32 s8, s4, s3
	s_addc_u32 s9, s5, 0
	s_and_b32 s2, s2, 15
	s_mul_i32 s2, s2, 0x1800
	s_mov_b32 m0, s2
	s_nop 0
	global_load_lds_dwordx4 v20, s[8:9]
	s_add_i32 m0, s2, 0x400
	s_nop 0
	global_load_lds_dwordx4 v21, s[8:9]
	s_add_i32 m0, s2, 0x800
	s_nop 0
	global_load_lds_dwordx4 v22, s[8:9]
	s_add_i32 m0, s2, 0xc00
	s_nop 0
	global_load_lds_dwordx4 v23, s[8:9]
	s_add_i32 m0, s2, 0x1000
	s_nop 0
	global_load_lds_dwordx4 v24, s[8:9]
	s_add_i32 m0, s2, 0x1400
	s_nop 0
	global_load_lds_dwordx4 v25, s[8:9]
.Lld_next:
	s_add_u32 s14, s14, 1
	s_cmp_le_u32 s14, 0x200
	s_cbranch_scc1 .Lld_loop
	s_waitcnt vmcnt(0)
